# attention loop: exp/convert groups software-pipelined into the PV MFMA gaps (P operands produced one group ahead)
# baseline (speedup 1.0000x reference)
.LBB0_266:
	s_add_i32 s4, s4, 1
	s_add_i32 s5, s12, s4
	s_cmp_eq_u32 s5, 2
	v_add_f32_e32 v185, v185, v205
	s_waitcnt lgkmcnt(0)
	s_barrier
	s_cbranch_scc1 .LBB0_272

.LBB0_269:
	v_exp_f32_e32 v180, v82
	v_exp_f32_e32 v178, v83
	v_exp_f32_e32 v176, v84
	v_exp_f32_e32 v174, v85
	v_exp_f32_e32 v172, v86
	v_exp_f32_e32 v170, v87
	v_exp_f32_e32 v168, v88
	v_exp_f32_e32 v88, v89
	v_add3_u32 v230, s5, v150, v186
	v_cvt_pk_bf16_f32 v242, v180, v178
	v_cvt_pk_bf16_f32 v243, v176, v174
	v_cvt_pk_bf16_f32 v244, v172, v170
	v_cvt_pk_bf16_f32 v245, v168, v88
	v_add_u32_e32 v246, 0x4800, v230
	v_add_u32_e32 v247, 0x5800, v230
	v_add_u32_e32 v248, 0x6800, v230
	v_add_u32_e32 v249, 0x7800, v230
	ds_read2_b64 v[192:195], v246 offset0:0 offset1:2
	ds_read2_b64 v[206:209], v247 offset0:32 offset1:34
	ds_read2_b64 v[210:213], v248 offset0:64 offset1:66
	ds_read2_b64 v[222:225], v249 offset0:96 offset1:98
	s_waitcnt lgkmcnt(3)
	v_mfma_f32_32x32x16_bf16 v[50:65], v[192:195], v[242:245], v[50:65]
	ds_read2_b64 v[192:195], v246 offset0:8 offset1:10
	v_exp_f32_e32 v181, v66
	v_exp_f32_e32 v179, v67
	s_add_i32 s5, s4, -1
	s_bitcmp1_b32 s5, 0
	s_cselect_b32 s5, 0x8c00, 0
	s_waitcnt lgkmcnt(3)
	v_mfma_f32_32x32x16_bf16 v[34:49], v[206:209], v[242:245], v[34:49]
	ds_read2_b64 v[206:209], v247 offset0:40 offset1:42
	v_exp_f32_e32 v177, v68
	v_exp_f32_e32 v175, v69
	v_lshlrev_b32_e32 v250, 1, v153
	v_add3_u32 v250, s5, v250, v152
	s_waitcnt lgkmcnt(3)
	v_mfma_f32_32x32x16_bf16 v[18:33], v[210:213], v[242:245], v[18:33]
	ds_read2_b64 v[210:213], v248 offset0:72 offset1:74
	v_exp_f32_e32 v173, v70
	v_exp_f32_e32 v171, v71
	s_waitcnt vmcnt(0)
	ds_write_b128 v250, v[114:117]
	s_waitcnt lgkmcnt(4)
	v_mfma_f32_32x32x16_bf16 v[2:17], v[222:225], v[242:245], v[2:17]
	ds_read2_b64 v[222:225], v249 offset0:104 offset1:106
	v_exp_f32_e32 v169, v72
	v_exp_f32_e32 v89, v73
	v_cvt_pk_bf16_f32 v238, v181, v179
	v_cvt_pk_bf16_f32 v239, v177, v175
	v_cvt_pk_bf16_f32 v240, v173, v171
	v_cvt_pk_bf16_f32 v241, v169, v89
	ds_write_b128 v250, v[118:121] offset:4608
	s_waitcnt lgkmcnt(5)
	v_mfma_f32_32x32x16_bf16 v[50:65], v[192:195], v[238:241], v[50:65]
	ds_read2_b64 v[192:195], v246 offset0:4 offset1:6
	v_exp_f32_e32 v86, v90
	v_exp_f32_e32 v84, v91
	ds_write_b128 v250, v[122:125] offset:9216
	v_add_f32_e32 v205, v180, v178
	v_add_f32_e32 v205, v205, v176
	v_add_f32_e32 v205, v205, v174
	s_waitcnt lgkmcnt(6)
	v_mfma_f32_32x32x16_bf16 v[34:49], v[206:209], v[238:241], v[34:49]
	ds_read2_b64 v[206:209], v247 offset0:36 offset1:38
	v_exp_f32_e32 v82, v92
	v_exp_f32_e32 v229, v93
	ds_write_b128 v250, v[126:129] offset:13824
	v_add_f32_e32 v205, v205, v172
	v_add_f32_e32 v205, v205, v170
	v_add_f32_e32 v205, v205, v168
	s_waitcnt lgkmcnt(7)
	v_mfma_f32_32x32x16_bf16 v[18:33], v[210:213], v[238:241], v[18:33]
	ds_read2_b64 v[210:213], v248 offset0:68 offset1:70
	v_exp_f32_e32 v72, v94
	v_exp_f32_e32 v70, v95
	v_lshlrev_b32_e32 v251, 1, v182
	v_add3_u32 v251, s5, v251, v152
	v_add_f32_e32 v205, v205, v88
	v_add_f32_e32 v215, v181, v179
	v_add_f32_e32 v215, v215, v177
	s_waitcnt lgkmcnt(6)
	v_mfma_f32_32x32x16_bf16 v[2:17], v[222:225], v[238:241], v[2:17]
	ds_read2_b64 v[222:225], v249 offset0:100 offset1:102
	v_exp_f32_e32 v68, v96
	v_exp_f32_e32 v66, v97
	v_cvt_pk_bf16_f32 v90, v86, v84
	v_cvt_pk_bf16_f32 v91, v82, v229
	v_cvt_pk_bf16_f32 v92, v72, v70
	v_cvt_pk_bf16_f32 v93, v68, v66
	v_add_u32_e32 v214, 0x4800, v251
	ds_write2_b64 v214, v[130:131], v[132:133] offset1:1
	s_waitcnt lgkmcnt(6)
	v_mfma_f32_32x32x16_bf16 v[50:65], v[192:195], v[90:93], v[50:65]
	ds_read2_b64 v[192:195], v246 offset0:12 offset1:14
	v_exp_f32_e32 v87, v74
	v_exp_f32_e32 v85, v75
	v_add_u32_e32 v214, 0x5900, v251
	ds_write2_b64 v214, v[134:135], v[136:137] offset1:1
	v_add_f32_e32 v215, v215, v175
	v_add_f32_e32 v215, v215, v173
	v_add_f32_e32 v215, v215, v171
	s_waitcnt lgkmcnt(6)
	v_mfma_f32_32x32x16_bf16 v[34:49], v[206:209], v[90:93], v[34:49]
	ds_read2_b64 v[206:209], v247 offset0:44 offset1:46
	v_exp_f32_e32 v83, v76
	v_exp_f32_e32 v75, v77
	v_add_u32_e32 v214, 0x6a00, v251
	ds_write2_b64 v214, v[138:139], v[140:141] offset1:1
	v_add_f32_e32 v215, v215, v169
	v_add_f32_e32 v215, v215, v89
	v_add_f32_e32 v218, v86, v84
	s_waitcnt lgkmcnt(6)
	v_mfma_f32_32x32x16_bf16 v[18:33], v[210:213], v[90:93], v[18:33]
	ds_read2_b64 v[210:213], v248 offset0:76 offset1:78
	v_exp_f32_e32 v73, v78
	v_exp_f32_e32 v71, v79
	v_add_u32_e32 v214, 0x7b00, v251
	ds_write2_b64 v214, v[142:143], v[144:145] offset1:1
	v_add_f32_e32 v218, v218, v82
	v_add_f32_e32 v218, v218, v229
	v_add_f32_e32 v218, v218, v72
	s_waitcnt lgkmcnt(7)
	v_mfma_f32_32x32x16_bf16 v[2:17], v[222:225], v[90:93], v[2:17]
	ds_read2_b64 v[222:225], v249 offset0:108 offset1:110
	v_exp_f32_e32 v69, v80
	v_exp_f32_e32 v67, v81
	v_cvt_pk_bf16_f32 v188, v87, v85
	v_cvt_pk_bf16_f32 v189, v83, v75
	v_cvt_pk_bf16_f32 v190, v73, v71
	v_cvt_pk_bf16_f32 v191, v69, v67
	global_load_dwordx4 v[114:117], v[156:157], off offset:-2048
	global_load_dwordx4 v[118:121], v[156:157], off offset:2048
	s_waitcnt lgkmcnt(6)
	v_mfma_f32_32x32x16_bf16 v[50:65], v[192:195], v[188:191], v[50:65]
	global_load_dwordx4 v[122:125], v[158:159], off offset:-2048
	global_load_dwordx4 v[126:129], v[158:159], off offset:2048
	v_add_f32_e32 v218, v218, v70
	v_add_f32_e32 v218, v218, v68
	v_add_f32_e32 v218, v218, v66
	v_add_f32_e32 v219, v87, v85
	v_add_f32_e32 v219, v219, v83
	v_add_f32_e32 v219, v219, v75
	v_add_f32_e32 v219, v219, v73
	v_add_f32_e32 v219, v219, v71
	v_add_f32_e32 v219, v219, v69
	s_waitcnt lgkmcnt(4)
	v_mfma_f32_32x32x16_bf16 v[34:49], v[206:209], v[188:191], v[34:49]
	global_load_dwordx4 v[130:133], v[160:161], off offset:384
	global_load_dwordx4 v[134:137], v[162:163], off offset:384
	v_add_f32_e32 v219, v219, v67
	v_add_f32_e32 v205, v205, v215
	v_add_f32_e32 v218, v218, v219
	v_add_f32_e32 v205, v205, v218
	s_waitcnt lgkmcnt(2)
	v_mfma_f32_32x32x16_bf16 v[18:33], v[210:213], v[188:191], v[18:33]
	global_load_dwordx4 v[138:141], v[164:165], off offset:384
	global_load_dwordx4 v[142:145], v[166:167], off offset:384
	s_waitcnt lgkmcnt(0)
	v_mfma_f32_32x32x16_bf16 v[2:17], v[222:225], v[188:191], v[2:17]
	s_branch .LBB0_266
